# final-layer y epilogue only: final_g vectors loaded once instead of before each of the 32 row stores
# baseline (speedup 1.0000x reference)
.LBB0_290:
	s_or_b64 exec, exec, s[16:17]
	v_lshlrev_b64 v[2:3], 2, v[146:147]
	s_waitcnt lgkmcnt(0)
	v_lshl_add_u64 v[0:1], s[14:15], 0, v[2:3]
	s_barrier
	global_load_dwordx4 v[214:217], v[0:1], off
	global_load_dwordx4 v[218:221], v[0:1], off offset:64
	global_load_dwordx4 v[222:225], v[0:1], off offset:512
	global_load_dwordx4 v[226:229], v[0:1], off offset:576
	v_lshl_add_u32 v5, v113, 2, 0
	v_add_u32_e32 v144, 0x1000, v5
	ds_read2_b32 v[10:11], v144 offset1:16
	v_add_u32_e32 v4, s61, v113
	v_ashrrev_i32_e32 v5, 31, v4
	v_readlane_b32 s16, v254, 26
	v_lshlrev_b64 v[12:13], 12, v[4:5]
	v_readlane_b32 s18, v254, 28
	v_readlane_b32 s19, v254, 29
	s_waitcnt lgkmcnt(0)
	v_pk_mul_f32 v[14:15], v[126:127], v[10:11] op_sel_hi:[1,0]
	v_pk_mul_f32 v[142:143], v[128:129], v[10:11] op_sel_hi:[1,0]
	v_lshl_add_u64 v[12:13], s[18:19], 0, v[12:13]
	v_lshl_add_u64 v[12:13], v[12:13], 0, v[2:3]
	s_mov_b64 s[0:1], 0
	v_readlane_b32 s17, v254, 27
	s_waitcnt vmcnt(0)
	v_pk_mul_f32 v[8:9], v[216:217], v[142:143]
	v_pk_mul_f32 v[6:7], v[214:215], v[14:15]
	global_store_dwordx4 v[12:13], v[6:9], off
	v_pk_mul_f32 v[14:15], v[122:123], v[10:11] op_sel_hi:[1,0]
	v_pk_mul_f32 v[142:143], v[124:125], v[10:11] op_sel_hi:[1,0]
	v_pk_mul_f32 v[6:7], v[218:219], v[14:15]
	v_pk_mul_f32 v[8:9], v[220:221], v[142:143]
	global_store_dwordx4 v[12:13], v[6:9], off offset:64
	v_pk_mul_f32 v[14:15], v[118:119], v[10:11] op_sel_hi:[1,0]
	v_pk_mul_f32 v[142:143], v[120:121], v[10:11] op_sel_hi:[1,0]
	v_pk_mul_f32 v[6:7], v[14:15], v[222:223]
	v_pk_mul_f32 v[8:9], v[142:143], v[224:225]
	global_store_dwordx4 v[12:13], v[6:9], off offset:512
	v_pk_mul_f32 v[14:15], v[150:151], v[10:11] op_sel_hi:[1,0]
	v_pk_mul_f32 v[142:143], v[148:149], v[10:11] op_sel_hi:[1,0]
	v_mov_b32_e32 v10, v11
	v_pk_mul_f32 v[8:9], v[142:143], v[228:229]
	v_pk_mul_f32 v[6:7], v[14:15], v[226:227]
	global_store_dwordx4 v[12:13], v[6:9], off offset:576
	v_add_u32_e32 v12, 16, v4
	v_ashrrev_i32_e32 v13, 31, v12
	v_lshlrev_b64 v[12:13], 12, v[12:13]
	v_lshl_add_u64 v[12:13], s[18:19], 0, v[12:13]
	v_pk_mul_f32 v[14:15], v[110:111], v[10:11] op_sel_hi:[1,0]
	v_pk_mul_f32 v[142:143], v[108:109], v[10:11] op_sel_hi:[1,0]
	v_lshl_add_u64 v[12:13], v[12:13], 0, v[2:3]
	v_pk_mul_f32 v[8:9], v[216:217], v[142:143]
	v_pk_mul_f32 v[6:7], v[214:215], v[14:15]
	global_store_dwordx4 v[12:13], v[6:9], off
	v_pk_mul_f32 v[14:15], v[104:105], v[10:11] op_sel_hi:[1,0]
	v_pk_mul_f32 v[142:143], v[106:107], v[10:11] op_sel_hi:[1,0]
	v_pk_mul_f32 v[6:7], v[218:219], v[14:15]
	v_pk_mul_f32 v[8:9], v[220:221], v[142:143]
	global_store_dwordx4 v[12:13], v[6:9], off offset:64
	v_pk_mul_f32 v[14:15], v[100:101], v[10:11] op_sel_hi:[1,0]
	v_pk_mul_f32 v[142:143], v[102:103], v[10:11] op_sel_hi:[1,0]
	v_pk_mul_f32 v[6:7], v[14:15], v[222:223]
	v_pk_mul_f32 v[8:9], v[142:143], v[224:225]
	global_store_dwordx4 v[12:13], v[6:9], off offset:512
	v_pk_mul_f32 v[14:15], v[92:93], v[10:11] op_sel_hi:[1,0]
	v_pk_mul_f32 v[10:11], v[94:95], v[10:11] op_sel_hi:[1,0]
	v_pk_mul_f32 v[6:7], v[14:15], v[226:227]
	v_pk_mul_f32 v[8:9], v[10:11], v[228:229]
	global_store_dwordx4 v[12:13], v[6:9], off offset:576
	ds_read2_b32 v[12:13], v144 offset0:32 offset1:48
	v_add_u32_e32 v10, 32, v4
	v_ashrrev_i32_e32 v11, 31, v10
	v_lshlrev_b64 v[10:11], 12, v[10:11]
	v_lshl_add_u64 v[10:11], s[18:19], 0, v[10:11]
	s_waitcnt lgkmcnt(0)
	v_pk_mul_f32 v[14:15], v[96:97], v[12:13] op_sel_hi:[1,0]
	v_pk_mul_f32 v[142:143], v[98:99], v[12:13] op_sel_hi:[1,0]
	v_lshl_add_u64 v[10:11], v[10:11], 0, v[2:3]
	v_pk_mul_f32 v[8:9], v[216:217], v[142:143]
	v_pk_mul_f32 v[6:7], v[214:215], v[14:15]
	global_store_dwordx4 v[10:11], v[6:9], off
	v_pk_mul_f32 v[14:15], v[88:89], v[12:13] op_sel_hi:[1,0]
	v_pk_mul_f32 v[142:143], v[90:91], v[12:13] op_sel_hi:[1,0]
	v_pk_mul_f32 v[6:7], v[218:219], v[14:15]
	v_pk_mul_f32 v[8:9], v[220:221], v[142:143]
	global_store_dwordx4 v[10:11], v[6:9], off offset:64
	v_pk_mul_f32 v[14:15], v[84:85], v[12:13] op_sel_hi:[1,0]
	v_pk_mul_f32 v[142:143], v[86:87], v[12:13] op_sel_hi:[1,0]
	v_pk_mul_f32 v[6:7], v[14:15], v[222:223]
	v_pk_mul_f32 v[8:9], v[142:143], v[224:225]
	global_store_dwordx4 v[10:11], v[6:9], off offset:512
	v_pk_mul_f32 v[14:15], v[76:77], v[12:13] op_sel_hi:[1,0]
	v_pk_mul_f32 v[142:143], v[78:79], v[12:13] op_sel_hi:[1,0]
	v_mov_b32_e32 v12, v13
	v_pk_mul_f32 v[8:9], v[142:143], v[228:229]
	v_pk_mul_f32 v[6:7], v[14:15], v[226:227]
	global_store_dwordx4 v[10:11], v[6:9], off offset:576
	v_add_u32_e32 v10, 48, v4
	v_ashrrev_i32_e32 v11, 31, v10
	v_lshlrev_b64 v[10:11], 12, v[10:11]
	v_lshl_add_u64 v[10:11], s[18:19], 0, v[10:11]
	v_pk_mul_f32 v[14:15], v[80:81], v[12:13] op_sel_hi:[1,0]
	v_pk_mul_f32 v[142:143], v[82:83], v[12:13] op_sel_hi:[1,0]
	v_lshl_add_u64 v[10:11], v[10:11], 0, v[2:3]
	v_pk_mul_f32 v[8:9], v[216:217], v[142:143]
	v_pk_mul_f32 v[6:7], v[214:215], v[14:15]
	global_store_dwordx4 v[10:11], v[6:9], off
	v_pk_mul_f32 v[14:15], v[72:73], v[12:13] op_sel_hi:[1,0]
	v_pk_mul_f32 v[142:143], v[74:75], v[12:13] op_sel_hi:[1,0]
	v_pk_mul_f32 v[6:7], v[218:219], v[14:15]
	v_pk_mul_f32 v[8:9], v[220:221], v[142:143]
	global_store_dwordx4 v[10:11], v[6:9], off offset:64
	v_pk_mul_f32 v[14:15], v[68:69], v[12:13] op_sel_hi:[1,0]
	v_pk_mul_f32 v[142:143], v[70:71], v[12:13] op_sel_hi:[1,0]
	v_pk_mul_f32 v[6:7], v[14:15], v[222:223]
	v_pk_mul_f32 v[8:9], v[142:143], v[224:225]
	global_store_dwordx4 v[10:11], v[6:9], off offset:512
	v_pk_mul_f32 v[14:15], v[64:65], v[12:13] op_sel_hi:[1,0]
	v_pk_mul_f32 v[12:13], v[66:67], v[12:13] op_sel_hi:[1,0]
	v_pk_mul_f32 v[6:7], v[14:15], v[226:227]
	v_pk_mul_f32 v[8:9], v[12:13], v[228:229]
	global_store_dwordx4 v[10:11], v[6:9], off offset:576
	ds_read2_b32 v[12:13], v144 offset0:128 offset1:144
	v_add_u32_e32 v10, 0x80, v4
	v_ashrrev_i32_e32 v11, 31, v10
	v_lshlrev_b64 v[10:11], 12, v[10:11]
	v_lshl_add_u64 v[10:11], s[18:19], 0, v[10:11]
	s_waitcnt lgkmcnt(0)
	v_pk_mul_f32 v[14:15], v[60:61], v[12:13] op_sel_hi:[1,0]
	v_pk_mul_f32 v[142:143], v[62:63], v[12:13] op_sel_hi:[1,0]
	v_lshl_add_u64 v[10:11], v[10:11], 0, v[2:3]
	v_pk_mul_f32 v[8:9], v[216:217], v[142:143]
	v_pk_mul_f32 v[6:7], v[214:215], v[14:15]
	global_store_dwordx4 v[10:11], v[6:9], off
	v_pk_mul_f32 v[14:15], v[56:57], v[12:13] op_sel_hi:[1,0]
	v_pk_mul_f32 v[142:143], v[58:59], v[12:13] op_sel_hi:[1,0]
	v_pk_mul_f32 v[6:7], v[218:219], v[14:15]
	v_pk_mul_f32 v[8:9], v[220:221], v[142:143]
	global_store_dwordx4 v[10:11], v[6:9], off offset:64
	v_pk_mul_f32 v[14:15], v[52:53], v[12:13] op_sel_hi:[1,0]
	v_pk_mul_f32 v[142:143], v[54:55], v[12:13] op_sel_hi:[1,0]
	v_pk_mul_f32 v[6:7], v[14:15], v[222:223]
	v_pk_mul_f32 v[8:9], v[142:143], v[224:225]
	global_store_dwordx4 v[10:11], v[6:9], off offset:512
	v_pk_mul_f32 v[14:15], v[44:45], v[12:13] op_sel_hi:[1,0]
	v_pk_mul_f32 v[142:143], v[46:47], v[12:13] op_sel_hi:[1,0]
	v_mov_b32_e32 v12, v13
	v_pk_mul_f32 v[8:9], v[142:143], v[228:229]
	v_pk_mul_f32 v[6:7], v[14:15], v[226:227]
	global_store_dwordx4 v[10:11], v[6:9], off offset:576
	v_add_u32_e32 v10, 0x90, v4
	v_ashrrev_i32_e32 v11, 31, v10
	v_lshlrev_b64 v[10:11], 12, v[10:11]
	v_lshl_add_u64 v[10:11], s[18:19], 0, v[10:11]
	v_pk_mul_f32 v[14:15], v[48:49], v[12:13] op_sel_hi:[1,0]
	v_pk_mul_f32 v[142:143], v[50:51], v[12:13] op_sel_hi:[1,0]
	v_lshl_add_u64 v[10:11], v[10:11], 0, v[2:3]
	v_pk_mul_f32 v[8:9], v[216:217], v[142:143]
	v_pk_mul_f32 v[6:7], v[214:215], v[14:15]
	global_store_dwordx4 v[10:11], v[6:9], off
	v_pk_mul_f32 v[14:15], v[40:41], v[12:13] op_sel_hi:[1,0]
	v_pk_mul_f32 v[142:143], v[42:43], v[12:13] op_sel_hi:[1,0]
	v_pk_mul_f32 v[6:7], v[218:219], v[14:15]
	v_pk_mul_f32 v[8:9], v[220:221], v[142:143]
	global_store_dwordx4 v[10:11], v[6:9], off offset:64
	v_pk_mul_f32 v[14:15], v[36:37], v[12:13] op_sel_hi:[1,0]
	v_pk_mul_f32 v[142:143], v[38:39], v[12:13] op_sel_hi:[1,0]
	v_pk_mul_f32 v[6:7], v[14:15], v[222:223]
	v_pk_mul_f32 v[8:9], v[142:143], v[224:225]
	global_store_dwordx4 v[10:11], v[6:9], off offset:512
	v_pk_mul_f32 v[14:15], v[28:29], v[12:13] op_sel_hi:[1,0]
	v_pk_mul_f32 v[12:13], v[30:31], v[12:13] op_sel_hi:[1,0]
	v_pk_mul_f32 v[6:7], v[14:15], v[226:227]
	v_pk_mul_f32 v[8:9], v[12:13], v[228:229]
	global_store_dwordx4 v[10:11], v[6:9], off offset:576
	ds_read2_b32 v[12:13], v144 offset0:160 offset1:176
	v_add_u32_e32 v10, 0xa0, v4
	v_ashrrev_i32_e32 v11, 31, v10
	v_lshlrev_b64 v[10:11], 12, v[10:11]
	v_lshl_add_u64 v[10:11], s[18:19], 0, v[10:11]
	s_waitcnt lgkmcnt(0)
	v_pk_mul_f32 v[14:15], v[32:33], v[12:13] op_sel_hi:[1,0]
	v_pk_mul_f32 v[142:143], v[34:35], v[12:13] op_sel_hi:[1,0]
	v_lshl_add_u64 v[10:11], v[10:11], 0, v[2:3]
	v_add_u32_e32 v4, 0xb0, v4
	v_ashrrev_i32_e32 v5, 31, v4
	v_lshlrev_b64 v[4:5], 12, v[4:5]
	v_lshl_add_u64 v[4:5], s[18:19], 0, v[4:5]
	v_pk_mul_f32 v[8:9], v[216:217], v[142:143]
	v_pk_mul_f32 v[6:7], v[214:215], v[14:15]
	global_store_dwordx4 v[10:11], v[6:9], off
	v_pk_mul_f32 v[14:15], v[24:25], v[12:13] op_sel_hi:[1,0]
	v_pk_mul_f32 v[142:143], v[26:27], v[12:13] op_sel_hi:[1,0]
	v_pk_mul_f32 v[6:7], v[218:219], v[14:15]
	v_pk_mul_f32 v[8:9], v[220:221], v[142:143]
	global_store_dwordx4 v[10:11], v[6:9], off offset:64
	v_pk_mul_f32 v[14:15], v[20:21], v[12:13] op_sel_hi:[1,0]
	v_pk_mul_f32 v[142:143], v[22:23], v[12:13] op_sel_hi:[1,0]
	v_pk_mul_f32 v[6:7], v[14:15], v[222:223]
	v_pk_mul_f32 v[8:9], v[142:143], v[224:225]
	global_store_dwordx4 v[10:11], v[6:9], off offset:512
	v_pk_mul_f32 v[14:15], v[116:117], v[12:13] op_sel_hi:[1,0]
	v_pk_mul_f32 v[142:143], v[114:115], v[12:13] op_sel_hi:[1,0]
	v_mov_b32_e32 v12, v13
	v_pk_mul_f32 v[8:9], v[142:143], v[228:229]
	v_pk_mul_f32 v[6:7], v[14:15], v[226:227]
	global_store_dwordx4 v[10:11], v[6:9], off offset:576
	v_lshl_add_u64 v[10:11], v[4:5], 0, v[2:3]
	v_pk_mul_f32 v[2:3], v[16:17], v[12:13] op_sel_hi:[1,0]
	v_pk_mul_f32 v[4:5], v[18:19], v[12:13] op_sel_hi:[1,0]
	v_pk_mul_f32 v[2:3], v[214:215], v[2:3]
	v_pk_mul_f32 v[4:5], v[216:217], v[4:5]
	global_store_dwordx4 v[10:11], v[2:5], off
	v_pk_mul_f32 v[6:7], v[138:139], v[12:13] op_sel_hi:[1,0]
	v_pk_mul_f32 v[8:9], v[140:141], v[12:13] op_sel_hi:[1,0]
	v_pk_mul_f32 v[2:3], v[218:219], v[6:7]
	v_pk_mul_f32 v[4:5], v[220:221], v[8:9]
	global_store_dwordx4 v[10:11], v[2:5], off offset:64
	v_pk_mul_f32 v[6:7], v[134:135], v[12:13] op_sel_hi:[1,0]
	v_pk_mul_f32 v[8:9], v[136:137], v[12:13] op_sel_hi:[1,0]
	v_pk_mul_f32 v[2:3], v[6:7], v[222:223]
	v_pk_mul_f32 v[4:5], v[8:9], v[224:225]
	global_store_dwordx4 v[10:11], v[2:5], off offset:512
	s_nop 1
	v_pk_mul_f32 v[6:7], v[132:133], v[12:13] op_sel_hi:[1,0]
	v_pk_mul_f32 v[4:5], v[130:131], v[12:13] op_sel_hi:[1,0]
	v_pk_mul_f32 v[2:3], v[6:7], v[228:229]
	v_pk_mul_f32 v[0:1], v[4:5], v[226:227]
	global_store_dwordx4 v[10:11], v[0:3], off offset:576
